# attention items remapped so that the q-blocks of one (sequence, head) run on the same XCD (shared K/V stay in that L2)
# speedup vs baseline: 1.0167x; 1.0037x over previous
.LBB0_775:
	s_and_b64 vcc, exec, s[22:23]
	s_cbranch_vccz .LBB0_785
	s_and_b32 s14, s0, 7
	s_lshr_b32 s15, s0, 3
	s_ff1_i32_b32 s16, s47
	s_add_i32 s17, s47, -1
	s_and_b32 s17, s15, s17
	s_lshr_b32 s15, s15, s16
	s_lshl_b32 s15, s15, 3
	s_add_i32 s15, s15, s14
	s_lshl_b32 s15, s15, s16
	s_or_b32 s0, s15, s17
	s_abs_i32 s12, s0
	v_readlane_b32 s13, v248, 25
	s_mul_hi_u32 s13, s12, s13
	s_mul_i32 s22, s13, s47
	s_sub_i32 s12, s12, s22
	s_ashr_i32 s1, s0, 31
	s_add_i32 s22, s13, 1
	s_sub_i32 s23, s12, s47
	s_cmp_ge_u32 s12, s47
	s_cselect_b32 s13, s22, s13
	s_cselect_b32 s12, s23, s12
	s_add_i32 s22, s13, 1
	s_cmp_ge_u32 s12, s47
	s_cselect_b32 s12, s22, s13
	s_xor_b32 s12, s12, s1
	s_sub_i32 s1, s12, s1
	s_mul_i32 s12, s1, s47
	s_sub_i32 s13, s0, s12
	s_and_b32 s12, s1, 7
	v_readlane_b32 s1, v248, 27
	s_mul_hi_u32 s1, s0, s1
	v_readlane_b32 s27, v248, 20
	s_mul_i32 s22, s1, s27
	s_sub_i32 s0, s0, s22
	s_add_i32 s22, s1, 1
	s_sub_i32 s23, s0, s27
	s_cmp_ge_u32 s0, s27
	s_cselect_b32 s1, s22, s1
	s_waitcnt vmcnt(4)
	v_mov_b32_e32 v14, v178
	s_cselect_b32 s0, s23, s0
	s_add_i32 s22, s1, 1
	s_cmp_ge_u32 s0, s27
	v_ashrrev_i32_e32 v0, 1, v14
	v_and_b32_e32 v15, 31, v14
	s_cselect_b32 s22, s22, s1
	s_lshl_b32 s0, s13, 7
	v_and_b32_e32 v0, 0xffffffe0, v0
	s_ashr_i32 s1, s0, 31
	v_ashrrev_i32_e32 v3, 31, v0
	v_or_b32_e32 v2, v0, v15
	v_lshl_add_u64 v[2:3], v[2:3], 0, s[0:1]
	v_mov_b32_e32 v0, s85
	v_mad_i64_i32 v[130:131], s[0:1], s22, v0, v[2:3]
	v_readlane_b32 s0, v249, 17
	v_readlane_b32 s1, v249, 18
	s_movk_i32 s13, 0x600
	v_bfe_u32 v16, v14, 5, 1
	v_mov_b64_e32 v[2:3], s[0:1]
	v_mad_u64_u32 v[2:3], s[0:1], v130, s13, v[2:3]
	v_mad_i32_i24 v3, v131, s13, v3
	s_mul_i32 s86, s12, 0xc0
	v_lshlrev_b32_e32 v17, 3, v14
	s_lshl_b32 s23, s12, 8
	v_readlane_b32 s0, v251, 37
	v_lshl_add_u64 v[2:3], v[2:3], 0, s[86:87]
	v_lshlrev_b32_e32 v0, 4, v16
	v_and_b32_e32 v18, 56, v17
	v_readlane_b32 s1, v251, 38
	s_add_u32 s0, s0, s23
	v_lshl_add_u64 v[2:3], v[2:3], 0, v[0:1]
	s_addc_u32 s1, s1, 0
	v_lshlrev_b32_e32 v0, 1, v18
	s_waitcnt vmcnt(3)
	v_ashrrev_i32_e32 v6, 3, v14
	v_readlane_b32 s27, v248, 21
	v_lshl_add_u64 v[4:5], s[0:1], 0, v[0:1]
	v_ashrrev_i32_e32 v7, 31, v6
	v_mov_b32_e32 v0, s27
	v_mad_i64_i32 v[8:9], s[0:1], s22, v0, v[6:7]
	v_lshlrev_b64 v[132:133], 11, v[8:9]
	v_lshl_add_u64 v[8:9], v[4:5], 0, v[132:133]
	global_load_dwordx4 v[66:69], v[8:9], off
	global_load_dwordx4 v[70:73], v[8:9], off offset:128
	v_add_u32_e32 v8, 0x100, v14
	v_ashrrev_i32_e32 v8, 3, v8
	v_ashrrev_i32_e32 v9, 31, v8
	s_waitcnt vmcnt(3)
	v_mad_i64_i32 v[10:11], s[0:1], s22, v0, v[8:9]
	v_lshlrev_b64 v[134:135], 11, v[10:11]
	v_lshl_add_u64 v[10:11], v[4:5], 0, v[134:135]
	global_load_dwordx4 v[74:77], v[10:11], off
	global_load_dwordx4 v[78:81], v[10:11], off offset:128
	v_ashrrev_i32_e32 v10, 2, v14
	v_ashrrev_i32_e32 v11, 31, v10
	v_mad_i64_i32 v[12:13], s[0:1], s22, v0, v[10:11]
	v_readlane_b32 s38, v249, 11
	v_and_b32_e32 v17, 24, v17
	v_lshlrev_b64 v[136:137], 6, v[12:13]
	v_readlane_b32 s39, v249, 12
	v_lshlrev_b32_e32 v0, 1, v17
	s_mul_hi_i32 s1, s22, s27
	v_lshl_add_u64 v[12:13], s[38:39], 0, v[136:137]
	s_mul_i32 s22, s22, s27
	v_lshl_add_u64 v[12:13], v[12:13], 0, v[0:1]
	s_or_b32 s0, s22, 64
	global_load_dwordx4 v[110:113], v[12:13], off
	global_load_dwordx4 v[82:85], v[2:3], off
	global_load_dwordx4 v[86:89], v[2:3], off offset:32
	global_load_dwordx4 v[90:93], v[2:3], off offset:64
	global_load_dwordx4 v[94:97], v[2:3], off offset:96
	global_load_dwordx4 v[98:101], v[2:3], off offset:128
	global_load_dwordx4 v[102:105], v[2:3], off offset:160
	v_lshl_add_u64 v[2:3], s[0:1], 0, v[6:7]
	v_lshlrev_b64 v[2:3], 11, v[2:3]
	v_lshl_add_u64 v[12:13], s[0:1], 0, v[8:9]
	v_lshl_add_u64 v[2:3], v[4:5], 0, v[2:3]
	v_lshlrev_b64 v[12:13], 11, v[12:13]
	global_load_dwordx4 v[106:109], v[2:3], off
	v_lshl_add_u64 v[4:5], v[4:5], 0, v[12:13]
	global_load_dwordx4 v[114:117], v[2:3], off offset:128
	global_load_dwordx4 v[118:121], v[4:5], off
	v_lshl_add_u64 v[2:3], s[0:1], 0, v[10:11]
	v_lshlrev_b64 v[2:3], 6, v[2:3]
	v_lshl_add_u64 v[2:3], s[38:39], 0, v[2:3]
	v_lshl_add_u64 v[2:3], v[2:3], 0, v[0:1]
	global_load_dwordx4 v[122:125], v[4:5], off offset:128
	global_load_dwordx4 v[126:129], v[2:3], off
	s_movk_i32 s0, 0x68
	v_mul_u32_u24_e32 v0, 0x48, v18
	v_mul_lo_u32 v2, v6, s0
	v_add_lshl_u32 v145, v2, v18, 1
	v_mul_lo_u32 v2, v8, s0
	v_mul_lo_u32 v0, v10, s0
	v_lshlrev_b32_e32 v19, 3, v16
	v_add_lshl_u32 v147, v2, v18, 1
	v_add_lshl_u32 v149, v0, v17, 1
	v_mul_u32_u24_e32 v0, 0x68, v15
	v_and_b32_e32 v2, 64, v186
	v_add_lshl_u32 v150, v19, v0, 1
	v_xor_b32_e32 v0, 32, v186
	v_add_u32_e32 v2, 64, v2
	v_cmp_lt_i32_e32 vcc, v0, v2
	v_lshlrev_b32_e32 v144, 2, v16
	v_mov_b32_e32 v154, 0
	v_cndmask_b32_e32 v0, v186, v0, vcc
	v_lshlrev_b32_e32 v151, 2, v0
	v_mul_u32_u24_e32 v0, 0x48, v15
	v_or_b32_e32 v0, v144, v0
	v_lshlrev_b32_e32 v152, 1, v0
	v_and_b32_e32 v0, 3, v14
	v_lshl_or_b32 v136, v0, 4, v136
	v_lshlrev_b32_e32 v0, 4, v14
	v_and_b32_e32 v0, 0x70, v0
	s_mov_b32 s13, 3
	v_mul_u32_u24_e32 v146, 0xc0, v6
	v_lshl_add_u32 v146, v18, 1, v146
	v_bfe_u32 v152, v15, 2, 2
	v_lshl_add_u32 v152, v16, 2, v152
	v_mul_u32_u24_e32 v148, 0xc0, v152
	v_lshrrev_b32_e32 v152, 4, v15
	v_lshl_add_u32 v148, v152, 5, v148
	v_and_b32_e32 v152, 3, v15
	v_lshl_add_u32 v148, v152, 3, v148
	v_or3_b32 v134, v134, s23, v0
	v_or3_b32 v132, v132, s23, v0
	v_mov_b32_e32 v213, 0xf149f2ca
	v_mov_b32_e32 v18, 0
	v_mov_b32_e32 v19, v154
	v_mov_b32_e32 v20, v154
	v_mov_b32_e32 v21, v154
	v_mov_b32_e32 v22, v154
	v_mov_b32_e32 v23, v154
	v_mov_b32_e32 v24, v154
	v_mov_b32_e32 v25, v154
	s_waitcnt vmcnt(16)
	v_mov_b32_e32 v26, v154
	v_mov_b32_e32 v27, v154
	v_mov_b32_e32 v28, v154
	v_mov_b32_e32 v29, v154
	v_mov_b32_e32 v30, v154
	v_mov_b32_e32 v31, v154
	v_mov_b32_e32 v32, v154
	v_mov_b32_e32 v33, v154
	v_mov_b32_e32 v2, 0
	v_mov_b32_e32 v3, v154
	v_mov_b32_e32 v4, v154
	v_mov_b32_e32 v5, v154
	v_mov_b32_e32 v6, v154
	v_mov_b32_e32 v7, v154
	v_mov_b32_e32 v8, v154
	v_mov_b32_e32 v9, v154
	v_mov_b32_e32 v10, v154
	v_mov_b32_e32 v11, v154
	v_mov_b32_e32 v12, v154
	v_mov_b32_e32 v13, v154
	v_mov_b32_e32 v14, v154
	v_mov_b32_e32 v15, v154
	v_mov_b32_e32 v16, v154
	v_mov_b32_e32 v17, v154
	s_barrier
	s_waitcnt vmcnt(15)
	ds_write_b128 v145, v[66:69]
	s_waitcnt vmcnt(14)
	ds_write_b128 v146, v[70:73] offset:13312
	s_waitcnt vmcnt(13)
	ds_write_b128 v147, v[74:77]
	s_waitcnt vmcnt(12)
	ds_write_b128 v146, v[78:81] offset:19456
	s_waitcnt vmcnt(11)
	ds_write_b128 v149, v[110:113] offset:128
	s_waitcnt lgkmcnt(0)
	s_barrier
	s_mov_b32 s23, 0xf149f2ca
